# in-proj (phase 1) output stores: nt streaming -> sc0 sc1 write-through (cache-allocatable for the spatial-gating/attention reads)
# baseline (speedup 1.0000x reference)
; DI u32x4 pk8(const f32x4& a, const f32x4& b) { u32x4 w; w.x = pk2(a[0], a[1]); w.y = pk2(a[2], a[3]); w.z = pk2(b[0], b[1]); w.w = pk2(b[2], b[3]); return w; }
; template <bool NT = false> DI void st_rows16(void* base, unsigned pitch_b, unsigned row0, unsigned col0, int fr, int fq, const u32x4& w0, const u32x4& w1) {
;   u32x4 x;
; #pragma unroll
;   for (int e = 0; e < 4; ++e) x[e] = (unsigned)__builtin_amdgcn_update_dpp(0, (int)w1[e], 0x128  , 0xf, 0xf, false);
;   const bool hi = fr >= 8;
;   u32x4 pa, pb;
; #pragma unroll
;   for (int e = 0; e < 4; ++e) { pa[e] = hi ? x[e] : w0[e]; pb[e] = hi ? w0[e] : x[e]; }
;   const unsigned ra = row0 + (unsigned)(fr & 7), ca = col0 + 8u * fq + (hi ? 32u : 0u), cb = col0 + 8u * fq + (hi ? 0u : 32u);
;   if (NT) { __builtin_nontemporal_store(pa, (u32x4*)((char*)base + (ra * pitch_b + ca * 2u))); __builtin_nontemporal_store(pb, (u32x4*)((char*)base + ((ra + 8u) * pitch_b + cb * 2u))); }
;   else { gst<u32x4>(base, ra * pitch_b + ca * 2u, pa); gst<u32x4>(base, (ra + 8u) * pitch_b + cb * 2u, pb); }
; }
;   DI void operator()(g8::Acc& acc, int pm, int pn, int wr, int wc, int fr, int fq) const {
;     ...
;           } else if (seg >= 5) {
; #pragma unroll
;             for (int e = 0; e < 4; ++e) { o0[e] = __builtin_amdgcn_rcpf(1.0f + __builtin_amdgcn_exp2f(-LOG2E * o0[e])); o1[e] = __builtin_amdgcn_rcpf(1.0f + __builtin_amdgcn_exp2f(-LOG2E * o1[e])); }
;           }
;           w[bj] = pk8(o0, o1);
;         }
;         st_rows16<true>(dst, ld * 2u, (unsigned)row0, col0, fr, fq, w[0], w[1]);
.Lrope_pf_skip1:
	global_store_dwordx4 v121, v[112:115], s[90:91] sc0 sc1
	v_cndmask_b32_e64 v119, v123, v119, s[6:7]
	s_and_b64 vcc, exec, s[10:11]
	v_or_b32_e32 v112, 8, v120
	v_lshl_add_u32 v112, v112, s19, v146
	s_mov_b64 s[0:1], -1
	global_store_dwordx4 v112, v[116:119], s[90:91] sc0 sc1
	s_cbranch_vccnz .LBB0_188
	s_and_b64 vcc, exec, s[8:9]
	s_cbranch_vccnz .LBB0_185
	s_andn2_b64 vcc, exec, s[88:89]
	v_mov_b32_e32 v115, v111
	v_mov_b32_e32 v114, v110
	v_mov_b32_e32 v113, v109
	v_mov_b32_e32 v112, v108
	v_mov_b32_e32 v119, v107
	v_mov_b32_e32 v118, v106
	v_mov_b32_e32 v117, v105
	v_mov_b32_e32 v116, v104
	s_cbranch_vccnz .LBB0_184
	v_mul_f32_e32 v113, 0xbfb8aa3b, v104
	v_exp_f32_e32 v113, v113
	v_mul_f32_e32 v114, 0xbfb8aa3b, v109
	v_mul_f32_e32 v115, 0xbfb8aa3b, v105
	v_exp_f32_e32 v114, v114
	v_exp_f32_e32 v115, v115
	v_add_f32_e32 v113, 1.0, v113
	v_rcp_f32_e32 v116, v113
	v_add_f32_e32 v113, 1.0, v114
	v_add_f32_e32 v114, 1.0, v115
	v_mul_f32_e32 v115, 0xbfb8aa3b, v110
	v_mul_f32_e32 v117, 0xbfb8aa3b, v106
	v_exp_f32_e32 v115, v115
	v_exp_f32_e32 v118, v117
	v_rcp_f32_e32 v117, v114
	v_mul_f32_e32 v112, 0xbfb8aa3b, v108
	v_add_f32_e32 v114, 1.0, v115
	v_add_f32_e32 v115, 1.0, v118
	v_mul_f32_e32 v118, 0xbfb8aa3b, v111
	v_exp_f32_e32 v119, v118
	v_mul_f32_e32 v118, 0xbfb8aa3b, v107
	v_exp_f32_e32 v112, v112
	v_exp_f32_e32 v120, v118
	v_rcp_f32_e32 v118, v115
	v_add_f32_e32 v115, 1.0, v119
	v_add_f32_e32 v112, 1.0, v112
	v_add_f32_e32 v119, 1.0, v120
	v_rcp_f32_e32 v112, v112
	v_rcp_f32_e32 v113, v113
	v_rcp_f32_e32 v114, v114
	v_rcp_f32_e32 v115, v115
	v_rcp_f32_e32 v119, v119

; DI u32x4 pk8(const f32x4& a, const f32x4& b) { u32x4 w; w.x = pk2(a[0], a[1]); w.y = pk2(a[2], a[3]); w.z = pk2(b[0], b[1]); w.w = pk2(b[2], b[3]); return w; }
; template <bool NT = false> DI void st_rows16(void* base, unsigned pitch_b, unsigned row0, unsigned col0, int fr, int fq, const u32x4& w0, const u32x4& w1) {
;   u32x4 x;
; #pragma unroll
;   for (int e = 0; e < 4; ++e) x[e] = (unsigned)__builtin_amdgcn_update_dpp(0, (int)w1[e], 0x128  , 0xf, 0xf, false);
;   const bool hi = fr >= 8;
;   u32x4 pa, pb;
; #pragma unroll
;   for (int e = 0; e < 4; ++e) { pa[e] = hi ? x[e] : w0[e]; pb[e] = hi ? w0[e] : x[e]; }
;   const unsigned ra = row0 + (unsigned)(fr & 7), ca = col0 + 8u * fq + (hi ? 32u : 0u), cb = col0 + 8u * fq + (hi ? 0u : 32u);
;   if (NT) { __builtin_nontemporal_store(pa, (u32x4*)((char*)base + (ra * pitch_b + ca * 2u))); __builtin_nontemporal_store(pb, (u32x4*)((char*)base + ((ra + 8u) * pitch_b + cb * 2u))); }
;   else { gst<u32x4>(base, ra * pitch_b + ca * 2u, pa); gst<u32x4>(base, (ra + 8u) * pitch_b + cb * 2u, pb); }
; }
;   DI void operator()(g8::Acc& acc, int pm, int pn, int wr, int wc, int fr, int fq) const {
;     ...
;           } else if (seg >= 5) {
; #pragma unroll
;             for (int e = 0; e < 4; ++e) { o0[e] = __builtin_amdgcn_rcpf(1.0f + __builtin_amdgcn_exp2f(-LOG2E * o0[e])); o1[e] = __builtin_amdgcn_rcpf(1.0f + __builtin_amdgcn_exp2f(-LOG2E * o1[e])); }
;           }
;           w[bj] = pk8(o0, o1);
;         }
;         st_rows16<true>(dst, ld * 2u, (unsigned)row0, col0, fr, fq, w[0], w[1]);
.Lrope_pf_skip2:
	global_store_dwordx4 v105, v[96:99], s[90:91] sc0 sc1
	v_cndmask_b32_e64 v103, v107, v103, s[6:7]
	s_and_b64 vcc, exec, s[10:11]
	v_or_b32_e32 v96, 8, v104
	v_lshl_add_u32 v96, v96, s19, v146
	s_mov_b64 s[0:1], -1
	global_store_dwordx4 v96, v[100:103], s[90:91] sc0 sc1
	s_cbranch_vccnz .LBB0_208
	s_and_b64 vcc, exec, s[8:9]
	s_cbranch_vccnz .LBB0_205
	s_andn2_b64 vcc, exec, s[88:89]
	v_mov_b32_e32 v99, v95
	v_mov_b32_e32 v98, v94
	v_mov_b32_e32 v97, v93
	v_mov_b32_e32 v96, v92
	v_mov_b32_e32 v103, v91
	v_mov_b32_e32 v102, v90
	v_mov_b32_e32 v101, v89
	v_mov_b32_e32 v100, v88
	s_cbranch_vccnz .LBB0_204
	v_mul_f32_e32 v97, 0xbfb8aa3b, v88
	v_exp_f32_e32 v97, v97
	v_mul_f32_e32 v98, 0xbfb8aa3b, v93
	v_mul_f32_e32 v99, 0xbfb8aa3b, v89
	v_exp_f32_e32 v98, v98
	v_exp_f32_e32 v99, v99
	v_add_f32_e32 v97, 1.0, v97
	v_rcp_f32_e32 v100, v97
	v_add_f32_e32 v97, 1.0, v98
	v_add_f32_e32 v98, 1.0, v99
	v_mul_f32_e32 v99, 0xbfb8aa3b, v94
	v_mul_f32_e32 v101, 0xbfb8aa3b, v90
	v_exp_f32_e32 v99, v99
	v_exp_f32_e32 v102, v101
	v_rcp_f32_e32 v101, v98
	v_mul_f32_e32 v96, 0xbfb8aa3b, v92
	v_add_f32_e32 v98, 1.0, v99
	v_add_f32_e32 v99, 1.0, v102
	v_mul_f32_e32 v102, 0xbfb8aa3b, v95
	v_exp_f32_e32 v103, v102
	v_mul_f32_e32 v102, 0xbfb8aa3b, v91
	v_exp_f32_e32 v96, v96
	v_exp_f32_e32 v104, v102
	v_rcp_f32_e32 v102, v99
	v_add_f32_e32 v99, 1.0, v103
	v_add_f32_e32 v96, 1.0, v96
	v_add_f32_e32 v103, 1.0, v104
	v_rcp_f32_e32 v96, v96
	v_rcp_f32_e32 v97, v97
	v_rcp_f32_e32 v98, v98
	v_rcp_f32_e32 v99, v99
	v_rcp_f32_e32 v103, v103

; DI u32x4 pk8(const f32x4& a, const f32x4& b) { u32x4 w; w.x = pk2(a[0], a[1]); w.y = pk2(a[2], a[3]); w.z = pk2(b[0], b[1]); w.w = pk2(b[2], b[3]); return w; }
; template <bool NT = false> DI void st_rows16(void* base, unsigned pitch_b, unsigned row0, unsigned col0, int fr, int fq, const u32x4& w0, const u32x4& w1) {
;   u32x4 x;
; #pragma unroll
;   for (int e = 0; e < 4; ++e) x[e] = (unsigned)__builtin_amdgcn_update_dpp(0, (int)w1[e], 0x128  , 0xf, 0xf, false);
;   const bool hi = fr >= 8;
;   u32x4 pa, pb;
; #pragma unroll
;   for (int e = 0; e < 4; ++e) { pa[e] = hi ? x[e] : w0[e]; pb[e] = hi ? w0[e] : x[e]; }
;   const unsigned ra = row0 + (unsigned)(fr & 7), ca = col0 + 8u * fq + (hi ? 32u : 0u), cb = col0 + 8u * fq + (hi ? 0u : 32u);
;   if (NT) { __builtin_nontemporal_store(pa, (u32x4*)((char*)base + (ra * pitch_b + ca * 2u))); __builtin_nontemporal_store(pb, (u32x4*)((char*)base + ((ra + 8u) * pitch_b + cb * 2u))); }
;   else { gst<u32x4>(base, ra * pitch_b + ca * 2u, pa); gst<u32x4>(base, (ra + 8u) * pitch_b + cb * 2u, pb); }
; }
;   DI void operator()(g8::Acc& acc, int pm, int pn, int wr, int wc, int fr, int fq) const {
;     ...
;           } else if (seg >= 5) {
; #pragma unroll
;             for (int e = 0; e < 4; ++e) { o0[e] = __builtin_amdgcn_rcpf(1.0f + __builtin_amdgcn_exp2f(-LOG2E * o0[e])); o1[e] = __builtin_amdgcn_rcpf(1.0f + __builtin_amdgcn_exp2f(-LOG2E * o1[e])); }
;           }
;           w[bj] = pk8(o0, o1);
;         }
;         st_rows16<true>(dst, ld * 2u, (unsigned)row0, col0, fr, fq, w[0], w[1]);
.Lrope_pf_skip3:
	global_store_dwordx4 v89, v[80:83], s[90:91] sc0 sc1
	v_cndmask_b32_e64 v87, v91, v87, s[6:7]
	s_and_b64 vcc, exec, s[10:11]
	v_or_b32_e32 v80, 8, v88
	v_lshl_add_u32 v80, v80, s19, v146
	s_mov_b64 s[0:1], -1
	global_store_dwordx4 v80, v[84:87], s[90:91] sc0 sc1
	s_cbranch_vccnz .LBB0_228
	s_and_b64 vcc, exec, s[8:9]
	s_cbranch_vccnz .LBB0_225
	s_andn2_b64 vcc, exec, s[88:89]
	v_mov_b32_e32 v83, v79
	v_mov_b32_e32 v82, v78
	v_mov_b32_e32 v81, v77
	v_mov_b32_e32 v80, v76
	v_mov_b32_e32 v87, v75
	v_mov_b32_e32 v86, v74
	v_mov_b32_e32 v85, v73
	v_mov_b32_e32 v84, v72
	s_cbranch_vccnz .LBB0_224
	v_mul_f32_e32 v81, 0xbfb8aa3b, v72
	v_exp_f32_e32 v81, v81
	v_mul_f32_e32 v82, 0xbfb8aa3b, v77
	v_mul_f32_e32 v83, 0xbfb8aa3b, v73
	v_exp_f32_e32 v82, v82
	v_exp_f32_e32 v83, v83
	v_add_f32_e32 v81, 1.0, v81
	v_rcp_f32_e32 v84, v81
	v_add_f32_e32 v81, 1.0, v82
	v_add_f32_e32 v82, 1.0, v83
	v_mul_f32_e32 v83, 0xbfb8aa3b, v78
	v_mul_f32_e32 v85, 0xbfb8aa3b, v74
	v_exp_f32_e32 v83, v83
	v_exp_f32_e32 v86, v85
	v_rcp_f32_e32 v85, v82
	v_mul_f32_e32 v80, 0xbfb8aa3b, v76
	v_add_f32_e32 v82, 1.0, v83
	v_add_f32_e32 v83, 1.0, v86
	v_mul_f32_e32 v86, 0xbfb8aa3b, v79
	v_exp_f32_e32 v87, v86
	v_mul_f32_e32 v86, 0xbfb8aa3b, v75
	v_exp_f32_e32 v80, v80
	v_exp_f32_e32 v88, v86
	v_rcp_f32_e32 v86, v83
	v_add_f32_e32 v83, 1.0, v87
	v_add_f32_e32 v80, 1.0, v80
	v_add_f32_e32 v87, 1.0, v88
	v_rcp_f32_e32 v80, v80
	v_rcp_f32_e32 v81, v81
	v_rcp_f32_e32 v82, v82
	v_rcp_f32_e32 v83, v83
	v_rcp_f32_e32 v87, v87

; DI u32x4 pk8(const f32x4& a, const f32x4& b) { u32x4 w; w.x = pk2(a[0], a[1]); w.y = pk2(a[2], a[3]); w.z = pk2(b[0], b[1]); w.w = pk2(b[2], b[3]); return w; }
; template <bool NT = false> DI void st_rows16(void* base, unsigned pitch_b, unsigned row0, unsigned col0, int fr, int fq, const u32x4& w0, const u32x4& w1) {
;   u32x4 x;
; #pragma unroll
;   for (int e = 0; e < 4; ++e) x[e] = (unsigned)__builtin_amdgcn_update_dpp(0, (int)w1[e], 0x128  , 0xf, 0xf, false);
;   const bool hi = fr >= 8;
;   u32x4 pa, pb;
; #pragma unroll
;   for (int e = 0; e < 4; ++e) { pa[e] = hi ? x[e] : w0[e]; pb[e] = hi ? w0[e] : x[e]; }
;   const unsigned ra = row0 + (unsigned)(fr & 7), ca = col0 + 8u * fq + (hi ? 32u : 0u), cb = col0 + 8u * fq + (hi ? 0u : 32u);
;   if (NT) { __builtin_nontemporal_store(pa, (u32x4*)((char*)base + (ra * pitch_b + ca * 2u))); __builtin_nontemporal_store(pb, (u32x4*)((char*)base + ((ra + 8u) * pitch_b + cb * 2u))); }
;   else { gst<u32x4>(base, ra * pitch_b + ca * 2u, pa); gst<u32x4>(base, (ra + 8u) * pitch_b + cb * 2u, pb); }
; }
;   DI void operator()(g8::Acc& acc, int pm, int pn, int wr, int wc, int fr, int fq) const {
;     ...
;           } else if (seg >= 5) {
; #pragma unroll
;             for (int e = 0; e < 4; ++e) { o0[e] = __builtin_amdgcn_rcpf(1.0f + __builtin_amdgcn_exp2f(-LOG2E * o0[e])); o1[e] = __builtin_amdgcn_rcpf(1.0f + __builtin_amdgcn_exp2f(-LOG2E * o1[e])); }
;           }
;           w[bj] = pk8(o0, o1);
;         }
;         st_rows16<true>(dst, ld * 2u, (unsigned)row0, col0, fr, fq, w[0], w[1]);
.Lrope_pf_skip4:
	global_store_dwordx4 v73, v[64:67], s[90:91] sc0 sc1
	v_cndmask_b32_e64 v71, v75, v71, s[6:7]
	s_and_b64 vcc, exec, s[10:11]
	v_or_b32_e32 v64, 8, v72
	v_lshl_add_u32 v64, v64, s19, v146
	s_mov_b64 s[0:1], -1
	global_store_dwordx4 v64, v[68:71], s[90:91] sc0 sc1
	s_cbranch_vccnz .LBB0_248
	s_and_b64 vcc, exec, s[8:9]
	s_cbranch_vccnz .LBB0_245
	s_andn2_b64 vcc, exec, s[88:89]
	v_mov_b32_e32 v67, v63
	v_mov_b32_e32 v66, v62
	v_mov_b32_e32 v65, v61
	v_mov_b32_e32 v64, v60
	v_mov_b32_e32 v71, v59
	v_mov_b32_e32 v70, v58
	v_mov_b32_e32 v69, v57
	v_mov_b32_e32 v68, v56
	s_cbranch_vccnz .LBB0_244
	v_mul_f32_e32 v65, 0xbfb8aa3b, v56
	v_exp_f32_e32 v65, v65
	v_mul_f32_e32 v66, 0xbfb8aa3b, v61
	v_mul_f32_e32 v67, 0xbfb8aa3b, v57
	v_exp_f32_e32 v66, v66
	v_exp_f32_e32 v67, v67
	v_add_f32_e32 v65, 1.0, v65
	v_rcp_f32_e32 v68, v65
	v_add_f32_e32 v65, 1.0, v66
	v_add_f32_e32 v66, 1.0, v67
	v_mul_f32_e32 v67, 0xbfb8aa3b, v62
	v_mul_f32_e32 v69, 0xbfb8aa3b, v58
	v_exp_f32_e32 v67, v67
	v_exp_f32_e32 v70, v69
	v_rcp_f32_e32 v69, v66
	v_mul_f32_e32 v64, 0xbfb8aa3b, v60
	v_add_f32_e32 v66, 1.0, v67
	v_add_f32_e32 v67, 1.0, v70
	v_mul_f32_e32 v70, 0xbfb8aa3b, v63
	v_exp_f32_e32 v71, v70
	v_mul_f32_e32 v70, 0xbfb8aa3b, v59
	v_exp_f32_e32 v64, v64
	v_exp_f32_e32 v72, v70
	v_rcp_f32_e32 v70, v67
	v_add_f32_e32 v67, 1.0, v71
	v_add_f32_e32 v64, 1.0, v64
	v_add_f32_e32 v71, 1.0, v72
	v_rcp_f32_e32 v64, v64
	v_rcp_f32_e32 v65, v65
	v_rcp_f32_e32 v66, v66
	v_rcp_f32_e32 v67, v67
	v_rcp_f32_e32 v71, v71

; DI u32x4 pk8(const f32x4& a, const f32x4& b) { u32x4 w; w.x = pk2(a[0], a[1]); w.y = pk2(a[2], a[3]); w.z = pk2(b[0], b[1]); w.w = pk2(b[2], b[3]); return w; }
; template <bool NT = false> DI void st_rows16(void* base, unsigned pitch_b, unsigned row0, unsigned col0, int fr, int fq, const u32x4& w0, const u32x4& w1) {
;   u32x4 x;
; #pragma unroll
;   for (int e = 0; e < 4; ++e) x[e] = (unsigned)__builtin_amdgcn_update_dpp(0, (int)w1[e], 0x128  , 0xf, 0xf, false);
;   const bool hi = fr >= 8;
;   u32x4 pa, pb;
; #pragma unroll
;   for (int e = 0; e < 4; ++e) { pa[e] = hi ? x[e] : w0[e]; pb[e] = hi ? w0[e] : x[e]; }
;   const unsigned ra = row0 + (unsigned)(fr & 7), ca = col0 + 8u * fq + (hi ? 32u : 0u), cb = col0 + 8u * fq + (hi ? 0u : 32u);
;   if (NT) { __builtin_nontemporal_store(pa, (u32x4*)((char*)base + (ra * pitch_b + ca * 2u))); __builtin_nontemporal_store(pb, (u32x4*)((char*)base + ((ra + 8u) * pitch_b + cb * 2u))); }
;   else { gst<u32x4>(base, ra * pitch_b + ca * 2u, pa); gst<u32x4>(base, (ra + 8u) * pitch_b + cb * 2u, pb); }
; }
;   DI void operator()(g8::Acc& acc, int pm, int pn, int wr, int wc, int fr, int fq) const {
;     ...
;           } else if (seg >= 5) {
; #pragma unroll
;             for (int e = 0; e < 4; ++e) { o0[e] = __builtin_amdgcn_rcpf(1.0f + __builtin_amdgcn_exp2f(-LOG2E * o0[e])); o1[e] = __builtin_amdgcn_rcpf(1.0f + __builtin_amdgcn_exp2f(-LOG2E * o1[e])); }
;           }
;           w[bj] = pk8(o0, o1);
;         }
;         st_rows16<true>(dst, ld * 2u, (unsigned)row0, col0, fr, fq, w[0], w[1]);
.Lrope_pf_skip5:
	global_store_dwordx4 v57, v[48:51], s[90:91] sc0 sc1
	v_cndmask_b32_e64 v55, v59, v55, s[6:7]
	s_and_b64 vcc, exec, s[10:11]
	v_or_b32_e32 v48, 8, v56
	v_lshl_add_u32 v48, v48, s19, v146
	s_mov_b64 s[0:1], -1
	global_store_dwordx4 v48, v[52:55], s[90:91] sc0 sc1
	s_cbranch_vccnz .LBB0_268
	s_and_b64 vcc, exec, s[8:9]
	s_cbranch_vccnz .LBB0_265
	s_andn2_b64 vcc, exec, s[88:89]
	v_mov_b32_e32 v51, v47
	v_mov_b32_e32 v50, v46
	v_mov_b32_e32 v49, v45
	v_mov_b32_e32 v48, v44
	v_mov_b32_e32 v55, v43
	v_mov_b32_e32 v54, v42
	v_mov_b32_e32 v53, v41
	v_mov_b32_e32 v52, v40
	s_cbranch_vccnz .LBB0_264
	v_mul_f32_e32 v49, 0xbfb8aa3b, v40
	v_exp_f32_e32 v49, v49
	v_mul_f32_e32 v50, 0xbfb8aa3b, v45
	v_mul_f32_e32 v51, 0xbfb8aa3b, v41
	v_exp_f32_e32 v50, v50
	v_exp_f32_e32 v51, v51
	v_add_f32_e32 v49, 1.0, v49
	v_rcp_f32_e32 v52, v49
	v_add_f32_e32 v49, 1.0, v50
	v_add_f32_e32 v50, 1.0, v51
	v_mul_f32_e32 v51, 0xbfb8aa3b, v46
	v_mul_f32_e32 v53, 0xbfb8aa3b, v42
	v_exp_f32_e32 v51, v51
	v_exp_f32_e32 v54, v53
	v_rcp_f32_e32 v53, v50
	v_mul_f32_e32 v48, 0xbfb8aa3b, v44
	v_add_f32_e32 v50, 1.0, v51
	v_add_f32_e32 v51, 1.0, v54
	v_mul_f32_e32 v54, 0xbfb8aa3b, v47
	v_exp_f32_e32 v55, v54
	v_mul_f32_e32 v54, 0xbfb8aa3b, v43
	v_exp_f32_e32 v48, v48
	v_exp_f32_e32 v56, v54
	v_rcp_f32_e32 v54, v51
	v_add_f32_e32 v51, 1.0, v55
	v_add_f32_e32 v48, 1.0, v48
	v_add_f32_e32 v55, 1.0, v56
	v_rcp_f32_e32 v48, v48
	v_rcp_f32_e32 v49, v49
	v_rcp_f32_e32 v50, v50
	v_rcp_f32_e32 v51, v51
	v_rcp_f32_e32 v55, v55

; DI u32x4 pk8(const f32x4& a, const f32x4& b) { u32x4 w; w.x = pk2(a[0], a[1]); w.y = pk2(a[2], a[3]); w.z = pk2(b[0], b[1]); w.w = pk2(b[2], b[3]); return w; }
; template <bool NT = false> DI void st_rows16(void* base, unsigned pitch_b, unsigned row0, unsigned col0, int fr, int fq, const u32x4& w0, const u32x4& w1) {
;   u32x4 x;
; #pragma unroll
;   for (int e = 0; e < 4; ++e) x[e] = (unsigned)__builtin_amdgcn_update_dpp(0, (int)w1[e], 0x128  , 0xf, 0xf, false);
;   const bool hi = fr >= 8;
;   u32x4 pa, pb;
; #pragma unroll
;   for (int e = 0; e < 4; ++e) { pa[e] = hi ? x[e] : w0[e]; pb[e] = hi ? w0[e] : x[e]; }
;   const unsigned ra = row0 + (unsigned)(fr & 7), ca = col0 + 8u * fq + (hi ? 32u : 0u), cb = col0 + 8u * fq + (hi ? 0u : 32u);
;   if (NT) { __builtin_nontemporal_store(pa, (u32x4*)((char*)base + (ra * pitch_b + ca * 2u))); __builtin_nontemporal_store(pb, (u32x4*)((char*)base + ((ra + 8u) * pitch_b + cb * 2u))); }
;   else { gst<u32x4>(base, ra * pitch_b + ca * 2u, pa); gst<u32x4>(base, (ra + 8u) * pitch_b + cb * 2u, pb); }
; }
;   DI void operator()(g8::Acc& acc, int pm, int pn, int wr, int wc, int fr, int fq) const {
;     ...
;           } else if (seg >= 5) {
; #pragma unroll
;             for (int e = 0; e < 4; ++e) { o0[e] = __builtin_amdgcn_rcpf(1.0f + __builtin_amdgcn_exp2f(-LOG2E * o0[e])); o1[e] = __builtin_amdgcn_rcpf(1.0f + __builtin_amdgcn_exp2f(-LOG2E * o1[e])); }
;           }
;           w[bj] = pk8(o0, o1);
;         }
;         st_rows16<true>(dst, ld * 2u, (unsigned)row0, col0, fr, fq, w[0], w[1]);
.Lrope_pf_skip6:
	global_store_dwordx4 v41, v[32:35], s[90:91] sc0 sc1
	v_cndmask_b32_e64 v39, v43, v39, s[6:7]
	s_and_b64 vcc, exec, s[10:11]
	v_or_b32_e32 v32, 8, v40
	v_lshl_add_u32 v32, v32, s19, v146
	s_mov_b64 s[0:1], -1
	global_store_dwordx4 v32, v[36:39], s[90:91] sc0 sc1
	s_cbranch_vccnz .LBB0_288
	s_and_b64 vcc, exec, s[8:9]
	s_cbranch_vccnz .LBB0_285
	s_andn2_b64 vcc, exec, s[88:89]
	v_mov_b32_e32 v35, v31
	v_mov_b32_e32 v34, v30
	v_mov_b32_e32 v33, v29
	v_mov_b32_e32 v32, v28
	v_mov_b32_e32 v39, v27
	v_mov_b32_e32 v38, v26
	v_mov_b32_e32 v37, v25
	v_mov_b32_e32 v36, v24
	s_cbranch_vccnz .LBB0_284
	v_mul_f32_e32 v33, 0xbfb8aa3b, v24
	v_exp_f32_e32 v33, v33
	v_mul_f32_e32 v34, 0xbfb8aa3b, v29
	v_mul_f32_e32 v35, 0xbfb8aa3b, v25
	v_exp_f32_e32 v34, v34
	v_exp_f32_e32 v35, v35
	v_add_f32_e32 v33, 1.0, v33
	v_rcp_f32_e32 v36, v33
	v_add_f32_e32 v33, 1.0, v34
	v_add_f32_e32 v34, 1.0, v35
	v_mul_f32_e32 v35, 0xbfb8aa3b, v30
	v_mul_f32_e32 v37, 0xbfb8aa3b, v26
	v_exp_f32_e32 v35, v35
	v_exp_f32_e32 v38, v37
	v_rcp_f32_e32 v37, v34
	v_mul_f32_e32 v32, 0xbfb8aa3b, v28
	v_add_f32_e32 v34, 1.0, v35
	v_add_f32_e32 v35, 1.0, v38
	v_mul_f32_e32 v38, 0xbfb8aa3b, v31
	v_exp_f32_e32 v39, v38
	v_mul_f32_e32 v38, 0xbfb8aa3b, v27
	v_exp_f32_e32 v32, v32
	v_exp_f32_e32 v40, v38
	v_rcp_f32_e32 v38, v35
	v_add_f32_e32 v35, 1.0, v39
	v_add_f32_e32 v32, 1.0, v32
	v_add_f32_e32 v39, 1.0, v40
	v_rcp_f32_e32 v32, v32
	v_rcp_f32_e32 v33, v33
	v_rcp_f32_e32 v34, v34
	v_rcp_f32_e32 v35, v35
	v_rcp_f32_e32 v39, v39

; DI u32x4 pk8(const f32x4& a, const f32x4& b) { u32x4 w; w.x = pk2(a[0], a[1]); w.y = pk2(a[2], a[3]); w.z = pk2(b[0], b[1]); w.w = pk2(b[2], b[3]); return w; }
; template <bool NT = false> DI void st_rows16(void* base, unsigned pitch_b, unsigned row0, unsigned col0, int fr, int fq, const u32x4& w0, const u32x4& w1) {
;   u32x4 x;
; #pragma unroll
;   for (int e = 0; e < 4; ++e) x[e] = (unsigned)__builtin_amdgcn_update_dpp(0, (int)w1[e], 0x128  , 0xf, 0xf, false);
;   const bool hi = fr >= 8;
;   u32x4 pa, pb;
; #pragma unroll
;   for (int e = 0; e < 4; ++e) { pa[e] = hi ? x[e] : w0[e]; pb[e] = hi ? w0[e] : x[e]; }
;   const unsigned ra = row0 + (unsigned)(fr & 7), ca = col0 + 8u * fq + (hi ? 32u : 0u), cb = col0 + 8u * fq + (hi ? 0u : 32u);
;   if (NT) { __builtin_nontemporal_store(pa, (u32x4*)((char*)base + (ra * pitch_b + ca * 2u))); __builtin_nontemporal_store(pb, (u32x4*)((char*)base + ((ra + 8u) * pitch_b + cb * 2u))); }
;   else { gst<u32x4>(base, ra * pitch_b + ca * 2u, pa); gst<u32x4>(base, (ra + 8u) * pitch_b + cb * 2u, pb); }
; }
;   DI void operator()(g8::Acc& acc, int pm, int pn, int wr, int wc, int fr, int fq) const {
;     ...
;           } else if (seg >= 5) {
; #pragma unroll
;             for (int e = 0; e < 4; ++e) { o0[e] = __builtin_amdgcn_rcpf(1.0f + __builtin_amdgcn_exp2f(-LOG2E * o0[e])); o1[e] = __builtin_amdgcn_rcpf(1.0f + __builtin_amdgcn_exp2f(-LOG2E * o1[e])); }
;           }
;           w[bj] = pk8(o0, o1);
;         }
;         st_rows16<true>(dst, ld * 2u, (unsigned)row0, col0, fr, fq, w[0], w[1]);
.Lrope_pf_skip7:
	global_store_dwordx4 v25, v[16:19], s[90:91] sc0 sc1
	v_cndmask_b32_e64 v23, v27, v23, s[6:7]
	s_and_b64 vcc, exec, s[10:11]
	v_or_b32_e32 v16, 8, v24
	v_lshl_add_u32 v16, v16, s19, v146
	s_mov_b64 s[0:1], -1
	global_store_dwordx4 v16, v[20:23], s[90:91] sc0 sc1
	s_cbranch_vccnz .LBB0_308
	s_and_b64 vcc, exec, s[8:9]
	s_cbranch_vccnz .LBB0_305
	s_andn2_b64 vcc, exec, s[88:89]
	v_mov_b32_e32 v19, v15
	v_mov_b32_e32 v18, v14
	v_mov_b32_e32 v17, v13
	v_mov_b32_e32 v16, v12
	v_mov_b32_e32 v23, v11
	v_mov_b32_e32 v22, v10
	v_mov_b32_e32 v21, v9
	v_mov_b32_e32 v20, v8
	s_cbranch_vccnz .LBB0_304
	v_mul_f32_e32 v17, 0xbfb8aa3b, v8
	v_exp_f32_e32 v17, v17
	v_mul_f32_e32 v18, 0xbfb8aa3b, v13
	v_mul_f32_e32 v19, 0xbfb8aa3b, v9
	v_exp_f32_e32 v18, v18
	v_exp_f32_e32 v19, v19
	v_add_f32_e32 v17, 1.0, v17
	v_rcp_f32_e32 v20, v17
	v_add_f32_e32 v17, 1.0, v18
	v_add_f32_e32 v18, 1.0, v19
	v_mul_f32_e32 v19, 0xbfb8aa3b, v14
	v_mul_f32_e32 v21, 0xbfb8aa3b, v10
	v_exp_f32_e32 v19, v19
	v_exp_f32_e32 v22, v21
	v_rcp_f32_e32 v21, v18
	v_mul_f32_e32 v16, 0xbfb8aa3b, v12
	v_add_f32_e32 v18, 1.0, v19
	v_add_f32_e32 v19, 1.0, v22
	v_mul_f32_e32 v22, 0xbfb8aa3b, v15
	v_exp_f32_e32 v23, v22
	v_mul_f32_e32 v22, 0xbfb8aa3b, v11
	v_exp_f32_e32 v16, v16
	v_exp_f32_e32 v24, v22
	v_rcp_f32_e32 v22, v19
	v_add_f32_e32 v19, 1.0, v23
	v_add_f32_e32 v16, 1.0, v16
	v_add_f32_e32 v23, 1.0, v24
	v_rcp_f32_e32 v16, v16
	v_rcp_f32_e32 v17, v17
	v_rcp_f32_e32 v18, v18
	v_rcp_f32_e32 v19, v19
	v_rcp_f32_e32 v23, v23

; DI unsigned pk2(float lo, float hi) { bf2_t v = __builtin_convertvector((f32x2){lo, hi}, bf2_t); return __builtin_bit_cast(unsigned, v); }
; DI u32x4 pk8(const f32x4& a, const f32x4& b) { u32x4 w; w.x = pk2(a[0], a[1]); w.y = pk2(a[2], a[3]); w.z = pk2(b[0], b[1]); w.w = pk2(b[2], b[3]); return w; }
; template <bool NT = false> DI void st_rows16(void* base, unsigned pitch_b, unsigned row0, unsigned col0, int fr, int fq, const u32x4& w0, const u32x4& w1) {
;   u32x4 x;
; #pragma unroll
;   for (int e = 0; e < 4; ++e) x[e] = (unsigned)__builtin_amdgcn_update_dpp(0, (int)w1[e], 0x128  , 0xf, 0xf, false);
;   const bool hi = fr >= 8;
;   u32x4 pa, pb;
; #pragma unroll
;   for (int e = 0; e < 4; ++e) { pa[e] = hi ? x[e] : w0[e]; pb[e] = hi ? w0[e] : x[e]; }
;   const unsigned ra = row0 + (unsigned)(fr & 7), ca = col0 + 8u * fq + (hi ? 32u : 0u), cb = col0 + 8u * fq + (hi ? 0u : 32u);
;   if (NT) { __builtin_nontemporal_store(pa, (u32x4*)((char*)base + (ra * pitch_b + ca * 2u))); __builtin_nontemporal_store(pb, (u32x4*)((char*)base + ((ra + 8u) * pitch_b + cb * 2u))); }
;   else { gst<u32x4>(base, ra * pitch_b + ca * 2u, pa); gst<u32x4>(base, (ra + 8u) * pitch_b + cb * 2u, pb); }
; }
;   DI void operator()(g8::Acc& acc, int pm, int pn, int wr, int wc, int fr, int fq) const {
;     ...
;           w[bj] = pk8(o0, o1);
;         }
;         st_rows16<true>(dst, ld * 2u, (unsigned)row0, col0, fr, fq, w[0], w[1]);
.LBB0_320:
	v_cvt_pk_bf16_f32 v0, v8, v9
	v_mov_b32_e32 v8, 0
	v_cvt_pk_bf16_f32 v1, v16, v17
	v_cvt_pk_bf16_f32 v4, v10, v11
	v_cvt_pk_bf16_f32 v5, v12, v13
	v_cvt_pk_bf16_f32 v6, v14, v15
	v_mov_b32_dpp v8, v0 row_ror:8 row_mask:0xf bank_mask:0xf
	v_mov_b32_e32 v9, 0
	v_mov_b32_e32 v10, 0
	v_mov_b32_e32 v11, 0
	v_cvt_pk_bf16_f32 v7, v22, v23
	v_cvt_pk_bf16_f32 v3, v20, v21
	v_cvt_pk_bf16_f32 v2, v18, v19
	v_mov_b32_dpp v9, v4 row_ror:8 row_mask:0xf bank_mask:0xf
	v_mov_b32_dpp v10, v5 row_ror:8 row_mask:0xf bank_mask:0xf
	v_mov_b32_dpp v11, v6 row_ror:8 row_mask:0xf bank_mask:0xf
	v_cndmask_b32_e64 v0, v1, v8, s[6:7]
	v_cndmask_b32_e64 v4, v8, v1, s[6:7]
	v_or_b32_e32 v8, s18, v158
	v_cndmask_b32_e64 v1, v2, v9, s[6:7]
	v_cndmask_b32_e64 v5, v9, v2, s[6:7]
	v_cndmask_b32_e64 v2, v3, v10, s[6:7]
	v_cndmask_b32_e64 v6, v10, v3, s[6:7]
	v_cndmask_b32_e64 v3, v7, v11, s[6:7]
	v_lshl_add_u32 v9, v8, s19, v147
	global_store_dwordx4 v9, v[0:3], s[90:91] sc0 sc1
	v_cndmask_b32_e64 v7, v11, v7, s[6:7]
	s_andn2_b64 vcc, exec, s[64:65]
	v_or_b32_e32 v0, 8, v8
	v_lshl_add_u32 v0, v0, s19, v146
	s_mov_b64 s[0:1], -1
	global_store_dwordx4 v0, v[4:7], s[90:91] sc0 sc1
	s_cbranch_vccnz .LBB0_153
	s_andn2_b64 vcc, exec, s[50:51]
	s_cbranch_vccnz .LBB0_152
	s_barrier
	s_branch .LBB0_152
